# v24 + per-tile accumulator clears use v_mov_b64 (64 instead of 128 moves per tile)
# speedup vs baseline: 1.0599x; 1.0023x over previous
; template <class Epi>
; __device__ __forceinline__ void gemm_phase(LAS unsigned char* lds, const Gemm g, const Sched& S, const Epi& E) {
;     ...
; #pragma unroll
;         for (int a = 0; a < 2; ++a)
; #pragma unroll
;             for (int b = 0; b < 2; ++b)
; #pragma unroll
;                 for (int m = 0; m < 4; ++m)
; #pragma unroll
;                     for (int n = 0; n < 2; ++n) acc[a][b][m][n] = (f32x4){0.f, 0.f, 0.f, 0.f};
;         cur = nxt; cA = nA; cB = nB; ++ui;
.LBB0_173:
	v_mov_b64_e32 v[0:1], 0
	s_mov_b32 s57, s16
	s_mov_b32 s8, s18
	s_mov_b64 s[10:11], s[22:23]
	s_mov_b32 s56, s50
	v_mov_b64_e32 v[2:3], 0
	v_mov_b64_e32 v[4:5], 0
	v_mov_b64_e32 v[6:7], 0
	v_mov_b64_e32 v[8:9], 0
	v_mov_b64_e32 v[10:11], 0
	v_mov_b64_e32 v[12:13], 0
	v_mov_b64_e32 v[14:15], 0
	v_mov_b64_e32 v[16:17], 0
	v_mov_b64_e32 v[18:19], 0
	v_mov_b64_e32 v[20:21], 0
	v_mov_b64_e32 v[22:23], 0
	v_mov_b64_e32 v[24:25], 0
	v_mov_b64_e32 v[26:27], 0
	v_mov_b64_e32 v[28:29], 0
	v_mov_b64_e32 v[30:31], 0
	v_mov_b64_e32 v[32:33], 0
	v_mov_b64_e32 v[34:35], 0
	v_mov_b64_e32 v[36:37], 0
	v_mov_b64_e32 v[38:39], 0
	v_mov_b64_e32 v[40:41], 0
	v_mov_b64_e32 v[42:43], 0
	v_mov_b64_e32 v[44:45], 0
	v_mov_b64_e32 v[46:47], 0
	v_mov_b64_e32 v[48:49], 0
	v_mov_b64_e32 v[50:51], 0
	v_mov_b64_e32 v[52:53], 0
	v_mov_b64_e32 v[54:55], 0
	v_mov_b64_e32 v[56:57], 0
	v_mov_b64_e32 v[58:59], 0
	v_mov_b64_e32 v[60:61], 0
	v_mov_b64_e32 v[62:63], 0
	v_mov_b64_e32 v[64:65], 0
	v_mov_b64_e32 v[66:67], 0
	v_mov_b64_e32 v[68:69], 0
	v_mov_b64_e32 v[70:71], 0
	v_mov_b64_e32 v[72:73], 0
	v_mov_b64_e32 v[74:75], 0
	v_mov_b64_e32 v[76:77], 0
	v_mov_b64_e32 v[78:79], 0
	v_mov_b64_e32 v[80:81], 0
	v_mov_b64_e32 v[82:83], 0
	v_mov_b64_e32 v[84:85], 0
	v_mov_b64_e32 v[86:87], 0
	v_mov_b64_e32 v[88:89], 0
	v_mov_b64_e32 v[90:91], 0
	v_mov_b64_e32 v[92:93], 0
	v_mov_b64_e32 v[94:95], 0
	v_mov_b64_e32 v[96:97], 0
	v_mov_b64_e32 v[98:99], 0
	v_mov_b64_e32 v[100:101], 0
	v_mov_b64_e32 v[102:103], 0
	v_mov_b64_e32 v[104:105], 0
	v_mov_b64_e32 v[106:107], 0
	v_mov_b64_e32 v[108:109], 0
	v_mov_b64_e32 v[110:111], 0
	v_mov_b64_e32 v[112:113], 0
	v_mov_b64_e32 v[114:115], 0
	v_mov_b64_e32 v[116:117], 0
	v_mov_b64_e32 v[118:119], 0
	v_mov_b64_e32 v[120:121], 0
	v_mov_b64_e32 v[122:123], 0
	v_mov_b64_e32 v[124:125], 0
	v_mov_b64_e32 v[126:127], 0
	s_andn2_b64 vcc, exec, s[4:5]
	s_mov_b64 s[24:25], s[20:21]
	s_cbranch_vccz .LBB0_180

; template <class Epi>
; __device__ __forceinline__ void gemm_phase(LAS unsigned char* lds, const Gemm g, const Sched& S, const Epi& E) {
;     ...
; #pragma unroll
;         for (int a = 0; a < 2; ++a)
; #pragma unroll
;             for (int b = 0; b < 2; ++b)
; #pragma unroll
;                 for (int m = 0; m < 4; ++m)
; #pragma unroll
;                     for (int n = 0; n < 2; ++n) acc[a][b][m][n] = (f32x4){0.f, 0.f, 0.f, 0.f};
;         cur = nxt; cA = nA; cB = nB; ++ui;
.LBB0_243:
	v_mov_b64_e32 v[0:1], 0
	s_mov_b32 s52, s65
	s_mov_b32 s10, s66
	s_mov_b64 s[14:15], s[18:19]
	s_mov_b32 s43, s50
	v_mov_b64_e32 v[2:3], 0
	v_mov_b64_e32 v[4:5], 0
	v_mov_b64_e32 v[6:7], 0
	v_mov_b64_e32 v[8:9], 0
	v_mov_b64_e32 v[10:11], 0
	v_mov_b64_e32 v[12:13], 0
	v_mov_b64_e32 v[14:15], 0
	v_mov_b64_e32 v[16:17], 0
	v_mov_b64_e32 v[18:19], 0
	v_mov_b64_e32 v[20:21], 0
	v_mov_b64_e32 v[22:23], 0
	v_mov_b64_e32 v[24:25], 0
	v_mov_b64_e32 v[26:27], 0
	v_mov_b64_e32 v[28:29], 0
	v_mov_b64_e32 v[30:31], 0
	v_mov_b64_e32 v[32:33], 0
	v_mov_b64_e32 v[34:35], 0
	v_mov_b64_e32 v[36:37], 0
	v_mov_b64_e32 v[38:39], 0
	v_mov_b64_e32 v[40:41], 0
	v_mov_b64_e32 v[42:43], 0
	v_mov_b64_e32 v[44:45], 0
	v_mov_b64_e32 v[46:47], 0
	v_mov_b64_e32 v[48:49], 0
	v_mov_b64_e32 v[50:51], 0
	v_mov_b64_e32 v[52:53], 0
	v_mov_b64_e32 v[54:55], 0
	v_mov_b64_e32 v[56:57], 0
	v_mov_b64_e32 v[58:59], 0
	v_mov_b64_e32 v[60:61], 0
	v_mov_b64_e32 v[62:63], 0
	v_mov_b64_e32 v[64:65], 0
	v_mov_b64_e32 v[66:67], 0
	v_mov_b64_e32 v[68:69], 0
	v_mov_b64_e32 v[70:71], 0
	v_mov_b64_e32 v[72:73], 0
	v_mov_b64_e32 v[74:75], 0
	v_mov_b64_e32 v[76:77], 0
	v_mov_b64_e32 v[78:79], 0
	v_mov_b64_e32 v[80:81], 0
	v_mov_b64_e32 v[82:83], 0
	v_mov_b64_e32 v[84:85], 0
	v_mov_b64_e32 v[86:87], 0
	v_mov_b64_e32 v[88:89], 0
	v_mov_b64_e32 v[90:91], 0
	v_mov_b64_e32 v[92:93], 0
	v_mov_b64_e32 v[94:95], 0
	v_mov_b64_e32 v[96:97], 0
	v_mov_b64_e32 v[98:99], 0
	v_mov_b64_e32 v[100:101], 0
	v_mov_b64_e32 v[102:103], 0
	v_mov_b64_e32 v[104:105], 0
	v_mov_b64_e32 v[106:107], 0
	v_mov_b64_e32 v[108:109], 0
	v_mov_b64_e32 v[110:111], 0
	v_mov_b64_e32 v[112:113], 0
	v_mov_b64_e32 v[114:115], 0
	v_mov_b64_e32 v[116:117], 0
	v_mov_b64_e32 v[118:119], 0
	v_mov_b64_e32 v[120:121], 0
	v_mov_b64_e32 v[122:123], 0
	v_mov_b64_e32 v[124:125], 0
	v_mov_b64_e32 v[126:127], 0
	s_andn2_b64 vcc, exec, s[4:5]
	s_mov_b64 s[20:21], s[8:9]
	s_cbranch_vccz .LBB0_258

;     __device__ __forceinline__ size_t a_off(const Unit& u) const { return (size_t)(u.z >> 3) * zA_hi + (size_t)(u.z & 7) * zA_lo + (size_t)u.pm * aTile; }
;     __device__ __forceinline__ size_t b_off(const Unit& u) const { return (size_t)(u.z >> 3) * zB_hi + (size_t)u.pn * bTile; }
; template <class Epi>
; __device__ __forceinline__ void gemm_phase(LAS unsigned char* lds, const Gemm g, const Sched& S, const Epi& E) {
;     ...
;         const bool has_next = S.next(ui + 1, nxt);
;         const char* nA = has_next ? (const char*)g.A + S.a_off(nxt) : cA; const char* nB = has_next ? (const char*)g.Bt + S.b_off(nxt) : cB;
;     ...
; #pragma unroll
;         for (int a = 0; a < 2; ++a)
; #pragma unroll
;             for (int b = 0; b < 2; ++b)
; #pragma unroll
;                 for (int m = 0; m < 4; ++m)
; #pragma unroll
;                     for (int n = 0; n < 2; ++n) acc[a][b][m][n] = (f32x4){0.f, 0.f, 0.f, 0.f};
;         cur = nxt; cA = nA; cB = nB; ++ui;
.LBB0_377:
	s_ashr_i32 s53, s52, 31
	s_lshl_b64 s[10:11], s[52:53], 20
	v_cmp_lt_i64_e32 vcc, s[58:59], v[212:213]
	s_add_u32 s58, s48, s10
	s_addc_u32 s59, s49, s11
	s_and_b64 s[10:11], vcc, exec
	s_cselect_b32 s7, s59, s9
	s_cselect_b32 s10, s58, s8
	s_ashr_i32 s39, s38, 31
	s_lshl_b64 s[34:35], s[38:39], 20
	s_add_u32 s64, s12, s34
	s_addc_u32 s65, s13, s35
	s_and_b64 s[34:35], vcc, exec
	s_cselect_b32 s11, s65, s81
	s_cselect_b32 s34, s64, s80
	s_add_u32 s8, s8, 0x80080
	s_addc_u32 s9, s9, 0
	s_add_u32 s35, s80, 0x100
	v_mov_b64_e32 v[0:1], 0
	s_addc_u32 s39, s81, 0
	s_mov_b32 s50, -2
	v_mov_b64_e32 v[2:3], 0
	v_mov_b64_e32 v[4:5], 0
	v_mov_b64_e32 v[6:7], 0
	v_mov_b64_e32 v[8:9], 0
	v_mov_b64_e32 v[10:11], 0
	v_mov_b64_e32 v[12:13], 0
	v_mov_b64_e32 v[14:15], 0
	v_mov_b64_e32 v[16:17], 0
	v_mov_b64_e32 v[18:19], 0
	v_mov_b64_e32 v[20:21], 0
	v_mov_b64_e32 v[22:23], 0
	v_mov_b64_e32 v[24:25], 0
	v_mov_b64_e32 v[26:27], 0
	v_mov_b64_e32 v[28:29], 0
	v_mov_b64_e32 v[30:31], 0
	v_mov_b64_e32 v[64:65], 0
	v_mov_b64_e32 v[66:67], 0
	v_mov_b64_e32 v[68:69], 0
	v_mov_b64_e32 v[70:71], 0
	v_mov_b64_e32 v[72:73], 0
	v_mov_b64_e32 v[74:75], 0
	v_mov_b64_e32 v[76:77], 0
	v_mov_b64_e32 v[78:79], 0
	v_mov_b64_e32 v[80:81], 0
	v_mov_b64_e32 v[82:83], 0
	v_mov_b64_e32 v[84:85], 0
	v_mov_b64_e32 v[86:87], 0
	v_mov_b64_e32 v[88:89], 0
	v_mov_b64_e32 v[90:91], 0
	v_mov_b64_e32 v[92:93], 0
	v_mov_b64_e32 v[94:95], 0
	v_mov_b64_e32 v[32:33], 0
	v_mov_b64_e32 v[34:35], 0
	v_mov_b64_e32 v[36:37], 0
	v_mov_b64_e32 v[38:39], 0
	v_mov_b64_e32 v[40:41], 0
	v_mov_b64_e32 v[42:43], 0
	v_mov_b64_e32 v[44:45], 0
	v_mov_b64_e32 v[46:47], 0
	v_mov_b64_e32 v[48:49], 0
	v_mov_b64_e32 v[50:51], 0
	v_mov_b64_e32 v[52:53], 0
	v_mov_b64_e32 v[54:55], 0
	v_mov_b64_e32 v[56:57], 0
	v_mov_b64_e32 v[58:59], 0
	v_mov_b64_e32 v[60:61], 0
	v_mov_b64_e32 v[62:63], 0
	v_mov_b64_e32 v[96:97], 0
	v_mov_b64_e32 v[98:99], 0
	v_mov_b64_e32 v[100:101], 0
	v_mov_b64_e32 v[102:103], 0
	v_mov_b64_e32 v[104:105], 0
	v_mov_b64_e32 v[106:107], 0
	v_mov_b64_e32 v[108:109], 0
	v_mov_b64_e32 v[110:111], 0
	v_mov_b64_e32 v[112:113], 0
	v_mov_b64_e32 v[114:115], 0
	v_mov_b64_e32 v[116:117], 0
	v_mov_b64_e32 v[118:119], 0
	v_mov_b64_e32 v[120:121], 0
	v_mov_b64_e32 v[122:123], 0
	v_mov_b64_e32 v[124:125], 0
	v_mov_b64_e32 v[126:127], 0

;     __device__ __forceinline__ size_t a_off(const Unit& u) const { return (size_t)(u.z >> 3) * zA_hi + (size_t)(u.z & 7) * zA_lo + (size_t)u.pm * aTile; }
;     __device__ __forceinline__ size_t b_off(const Unit& u) const { return (size_t)(u.z >> 3) * zB_hi + (size_t)u.pn * bTile; }
; template <class Epi>
; __device__ __forceinline__ void gemm_phase(LAS unsigned char* lds, const Gemm g, const Sched& S, const Epi& E) {
;     ...
;         const bool has_next = S.next(ui + 1, nxt);
;         const char* nA = has_next ? (const char*)g.A + S.a_off(nxt) : cA; const char* nB = has_next ? (const char*)g.Bt + S.b_off(nxt) : cB;
;     ...
; #pragma unroll
;         for (int a = 0; a < 2; ++a)
; #pragma unroll
;             for (int b = 0; b < 2; ++b)
; #pragma unroll
;                 for (int m = 0; m < 4; ++m)
; #pragma unroll
;                     for (int n = 0; n < 2; ++n) acc[a][b][m][n] = (f32x4){0.f, 0.f, 0.f, 0.f};
;         cur = nxt; cA = nA; cB = nB; ++ui;
.LBB0_496:
	s_lshl_b64 s[10:11], s[18:19], 21
	s_add_u32 s18, s90, s10
	s_addc_u32 s19, s91, s11
	s_and_b64 s[10:11], s[38:39], exec
	s_cselect_b32 s7, s19, s37
	s_cselect_b32 s9, s18, s36
	s_add_u32 s24, s24, 0x80080
	s_addc_u32 s25, s25, 0
	s_add_u32 s10, s36, 0x100
	v_mov_b64_e32 v[0:1], 0
	s_addc_u32 s11, s37, 0
	s_mov_b32 s21, -2
	v_mov_b64_e32 v[2:3], 0
	v_mov_b64_e32 v[4:5], 0
	v_mov_b64_e32 v[6:7], 0
	v_mov_b64_e32 v[16:17], 0
	v_mov_b64_e32 v[18:19], 0
	v_mov_b64_e32 v[20:21], 0
	v_mov_b64_e32 v[22:23], 0
	v_mov_b64_e32 v[32:33], 0
	v_mov_b64_e32 v[34:35], 0
	v_mov_b64_e32 v[36:37], 0
	v_mov_b64_e32 v[38:39], 0
	v_mov_b64_e32 v[48:49], 0
	v_mov_b64_e32 v[50:51], 0
	v_mov_b64_e32 v[52:53], 0
	v_mov_b64_e32 v[54:55], 0
	v_mov_b64_e32 v[8:9], 0
	v_mov_b64_e32 v[10:11], 0
	v_mov_b64_e32 v[12:13], 0
	v_mov_b64_e32 v[14:15], 0
	v_mov_b64_e32 v[24:25], 0
	v_mov_b64_e32 v[26:27], 0
	v_mov_b64_e32 v[28:29], 0
	v_mov_b64_e32 v[30:31], 0
	v_mov_b64_e32 v[40:41], 0
	v_mov_b64_e32 v[42:43], 0
	v_mov_b64_e32 v[44:45], 0
	v_mov_b64_e32 v[46:47], 0
	v_mov_b64_e32 v[56:57], 0
	v_mov_b64_e32 v[58:59], 0
	v_mov_b64_e32 v[60:61], 0
	v_mov_b64_e32 v[62:63], 0
	v_mov_b64_e32 v[64:65], 0
	v_mov_b64_e32 v[66:67], 0
	v_mov_b64_e32 v[68:69], 0
	v_mov_b64_e32 v[70:71], 0
	v_mov_b64_e32 v[80:81], 0
	v_mov_b64_e32 v[82:83], 0
	v_mov_b64_e32 v[84:85], 0
	v_mov_b64_e32 v[86:87], 0
	v_mov_b64_e32 v[96:97], 0
	v_mov_b64_e32 v[98:99], 0
	v_mov_b64_e32 v[100:101], 0
	v_mov_b64_e32 v[102:103], 0
	v_mov_b64_e32 v[112:113], 0
	v_mov_b64_e32 v[114:115], 0
	v_mov_b64_e32 v[116:117], 0
	v_mov_b64_e32 v[118:119], 0
	v_mov_b64_e32 v[72:73], 0
	v_mov_b64_e32 v[74:75], 0
	v_mov_b64_e32 v[76:77], 0
	v_mov_b64_e32 v[78:79], 0
	v_mov_b64_e32 v[88:89], 0
	v_mov_b64_e32 v[90:91], 0
	v_mov_b64_e32 v[92:93], 0
	v_mov_b64_e32 v[94:95], 0
	v_mov_b64_e32 v[104:105], 0
	v_mov_b64_e32 v[106:107], 0
	v_mov_b64_e32 v[108:109], 0
	v_mov_b64_e32 v[110:111], 0
	v_mov_b64_e32 v[120:121], 0
	v_mov_b64_e32 v[122:123], 0
	v_mov_b64_e32 v[124:125], 0
	v_mov_b64_e32 v[126:127], 0

;     __device__ __forceinline__ size_t a_off(const Unit& u) const { return (size_t)(u.z >> 3) * zA_hi + (size_t)(u.z & 7) * zA_lo + (size_t)u.pm * aTile; }
;     __device__ __forceinline__ size_t b_off(const Unit& u) const { return (size_t)(u.z >> 3) * zB_hi + (size_t)u.pn * bTile; }
; template <class Epi>
; __device__ __forceinline__ void gemm_phase(LAS unsigned char* lds, const Gemm g, const Sched& S, const Epi& E) {
;     ...
;         const bool has_next = S.next(ui + 1, nxt);
;         const char* nA = has_next ? (const char*)g.A + S.a_off(nxt) : cA; const char* nB = has_next ? (const char*)g.Bt + S.b_off(nxt) : cB;
;     ...
; #pragma unroll
;         for (int a = 0; a < 2; ++a)
; #pragma unroll
;             for (int b = 0; b < 2; ++b)
; #pragma unroll
;                 for (int m = 0; m < 4; ++m)
; #pragma unroll
;                     for (int n = 0; n < 2; ++n) acc[a][b][m][n] = (f32x4){0.f, 0.f, 0.f, 0.f};
;         cur = nxt; cA = nA; cB = nB; ++ui;
.LBB0_519:
	s_ashr_i32 s59, s58, 31
	s_lshl_b64 s[34:35], s[58:59], 20
	v_cmp_lt_i64_e32 vcc, s[64:65], v[204:205]
	s_add_u32 s64, s48, s34
	s_addc_u32 s65, s49, s35
	s_and_b64 s[34:35], vcc, exec
	s_cselect_b32 s7, s65, s9
	s_cselect_b32 s34, s64, s8
	s_ashr_i32 s53, s52, 31
	s_lshl_b64 s[50:51], s[52:53], 20
	s_add_u32 s66, s14, s50
	s_addc_u32 s67, s15, s51
	s_and_b64 s[50:51], vcc, exec
	s_cselect_b32 s35, s67, s81
	s_cselect_b32 s50, s66, s80
	s_add_u32 s8, s8, 0x80080
	s_addc_u32 s9, s9, 0
	s_add_u32 s51, s80, 0x100
	v_mov_b64_e32 v[0:1], 0
	s_addc_u32 s53, s81, 0
	s_mov_b32 s59, -2
	v_mov_b64_e32 v[2:3], 0
	v_mov_b64_e32 v[4:5], 0
	v_mov_b64_e32 v[6:7], 0
	v_mov_b64_e32 v[8:9], 0
	v_mov_b64_e32 v[10:11], 0
	v_mov_b64_e32 v[12:13], 0
	v_mov_b64_e32 v[14:15], 0
	v_mov_b64_e32 v[16:17], 0
	v_mov_b64_e32 v[18:19], 0
	v_mov_b64_e32 v[20:21], 0
	v_mov_b64_e32 v[22:23], 0
	v_mov_b64_e32 v[24:25], 0
	v_mov_b64_e32 v[26:27], 0
	v_mov_b64_e32 v[28:29], 0
	v_mov_b64_e32 v[30:31], 0
	v_mov_b64_e32 v[64:65], 0
	v_mov_b64_e32 v[66:67], 0
	v_mov_b64_e32 v[68:69], 0
	v_mov_b64_e32 v[70:71], 0
	v_mov_b64_e32 v[72:73], 0
	v_mov_b64_e32 v[74:75], 0
	v_mov_b64_e32 v[76:77], 0
	v_mov_b64_e32 v[78:79], 0
	v_mov_b64_e32 v[80:81], 0
	v_mov_b64_e32 v[82:83], 0
	v_mov_b64_e32 v[84:85], 0
	v_mov_b64_e32 v[86:87], 0
	v_mov_b64_e32 v[88:89], 0
	v_mov_b64_e32 v[90:91], 0
	v_mov_b64_e32 v[92:93], 0
	v_mov_b64_e32 v[94:95], 0
	v_mov_b64_e32 v[32:33], 0
	v_mov_b64_e32 v[34:35], 0
	v_mov_b64_e32 v[36:37], 0
	v_mov_b64_e32 v[38:39], 0
	v_mov_b64_e32 v[40:41], 0
	v_mov_b64_e32 v[42:43], 0
	v_mov_b64_e32 v[44:45], 0
	v_mov_b64_e32 v[46:47], 0
	v_mov_b64_e32 v[48:49], 0
	v_mov_b64_e32 v[50:51], 0
	v_mov_b64_e32 v[52:53], 0
	v_mov_b64_e32 v[54:55], 0
	v_mov_b64_e32 v[56:57], 0
	v_mov_b64_e32 v[58:59], 0
	v_mov_b64_e32 v[60:61], 0
	v_mov_b64_e32 v[62:63], 0
	v_mov_b64_e32 v[96:97], 0
	v_mov_b64_e32 v[98:99], 0
	v_mov_b64_e32 v[100:101], 0
	v_mov_b64_e32 v[102:103], 0
	v_mov_b64_e32 v[104:105], 0
	v_mov_b64_e32 v[106:107], 0
	v_mov_b64_e32 v[108:109], 0
	v_mov_b64_e32 v[110:111], 0
	v_mov_b64_e32 v[112:113], 0
	v_mov_b64_e32 v[114:115], 0
	v_mov_b64_e32 v[116:117], 0
	v_mov_b64_e32 v[118:119], 0
	v_mov_b64_e32 v[120:121], 0
	v_mov_b64_e32 v[122:123], 0
	v_mov_b64_e32 v[124:125], 0
	v_mov_b64_e32 v[126:127], 0

; template <class Epi>
; __device__ __forceinline__ void gemm_phase(LAS unsigned char* lds, const Gemm g, const Sched& S, const Epi& E) {
;     ...
; #pragma unroll
;         for (int a = 0; a < 2; ++a)
; #pragma unroll
;             for (int b = 0; b < 2; ++b)
; #pragma unroll
;                 for (int m = 0; m < 4; ++m)
; #pragma unroll
;                     for (int n = 0; n < 2; ++n) acc[a][b][m][n] = (f32x4){0.f, 0.f, 0.f, 0.f};
;         cur = nxt; cA = nA; cB = nB; ++ui;
.LBB0_1959:
	v_mov_b64_e32 v[0:1], 0
	s_mov_b32 s53, s16
	s_mov_b32 s10, s18
	s_mov_b64 s[12:13], s[22:23]
	s_mov_b32 s52, s50
	v_mov_b64_e32 v[2:3], 0
	v_mov_b64_e32 v[4:5], 0
	v_mov_b64_e32 v[6:7], 0
	v_mov_b64_e32 v[8:9], 0
	v_mov_b64_e32 v[10:11], 0
	v_mov_b64_e32 v[12:13], 0
	v_mov_b64_e32 v[14:15], 0
	v_mov_b64_e32 v[16:17], 0
	v_mov_b64_e32 v[18:19], 0
	v_mov_b64_e32 v[20:21], 0
	v_mov_b64_e32 v[22:23], 0
	v_mov_b64_e32 v[24:25], 0
	v_mov_b64_e32 v[26:27], 0
	v_mov_b64_e32 v[28:29], 0
	v_mov_b64_e32 v[30:31], 0
	v_mov_b64_e32 v[32:33], 0
	v_mov_b64_e32 v[34:35], 0
	v_mov_b64_e32 v[36:37], 0
	v_mov_b64_e32 v[38:39], 0
	v_mov_b64_e32 v[40:41], 0
	v_mov_b64_e32 v[42:43], 0
	v_mov_b64_e32 v[44:45], 0
	v_mov_b64_e32 v[46:47], 0
	v_mov_b64_e32 v[48:49], 0
	v_mov_b64_e32 v[50:51], 0
	v_mov_b64_e32 v[52:53], 0
	v_mov_b64_e32 v[54:55], 0
	v_mov_b64_e32 v[56:57], 0
	v_mov_b64_e32 v[58:59], 0
	v_mov_b64_e32 v[60:61], 0
	v_mov_b64_e32 v[62:63], 0
	v_mov_b64_e32 v[64:65], 0
	v_mov_b64_e32 v[66:67], 0
	v_mov_b64_e32 v[68:69], 0
	v_mov_b64_e32 v[70:71], 0
	v_mov_b64_e32 v[72:73], 0
	v_mov_b64_e32 v[74:75], 0
	v_mov_b64_e32 v[76:77], 0
	v_mov_b64_e32 v[78:79], 0
	v_mov_b64_e32 v[80:81], 0
	v_mov_b64_e32 v[82:83], 0
	v_mov_b64_e32 v[84:85], 0
	v_mov_b64_e32 v[86:87], 0
	v_mov_b64_e32 v[88:89], 0
	v_mov_b64_e32 v[90:91], 0
	v_mov_b64_e32 v[92:93], 0
	v_mov_b64_e32 v[94:95], 0
	v_mov_b64_e32 v[96:97], 0
	v_mov_b64_e32 v[98:99], 0
	v_mov_b64_e32 v[100:101], 0
	v_mov_b64_e32 v[102:103], 0
	v_mov_b64_e32 v[104:105], 0
	v_mov_b64_e32 v[106:107], 0
	v_mov_b64_e32 v[108:109], 0
	v_mov_b64_e32 v[110:111], 0
	v_mov_b64_e32 v[112:113], 0
	v_mov_b64_e32 v[114:115], 0
	v_mov_b64_e32 v[116:117], 0
	v_mov_b64_e32 v[118:119], 0
	v_mov_b64_e32 v[120:121], 0
	v_mov_b64_e32 v[122:123], 0
	v_mov_b64_e32 v[124:125], 0
	v_mov_b64_e32 v[126:127], 0
	s_andn2_b64 vcc, exec, s[6:7]
	s_mov_b64 s[24:25], s[20:21]
	s_cbranch_vccz .LBB0_1970

; template <class Epi>
; __device__ __forceinline__ void gemm_phase(LAS unsigned char* lds, const Gemm g, const Sched& S, const Epi& E) {
;     ...
; #pragma unroll
;         for (int a = 0; a < 2; ++a)
; #pragma unroll
;             for (int b = 0; b < 2; ++b)
; #pragma unroll
;                 for (int m = 0; m < 4; ++m)
; #pragma unroll
;                     for (int n = 0; n < 2; ++n) acc[a][b][m][n] = (f32x4){0.f, 0.f, 0.f, 0.f};
;         cur = nxt; cA = nA; cB = nB; ++ui;
.LBB0_2084:
	v_mov_b64_e32 v[0:1], 0
	s_mov_b32 s58, s18
	s_mov_b32 s12, s20
	s_mov_b64 s[14:15], s[24:25]
	s_mov_b32 s57, s50
	v_mov_b64_e32 v[2:3], 0
	v_mov_b64_e32 v[4:5], 0
	v_mov_b64_e32 v[6:7], 0
	v_mov_b64_e32 v[8:9], 0
	v_mov_b64_e32 v[10:11], 0
	v_mov_b64_e32 v[12:13], 0
	v_mov_b64_e32 v[14:15], 0
	v_mov_b64_e32 v[16:17], 0
	v_mov_b64_e32 v[18:19], 0
	v_mov_b64_e32 v[20:21], 0
	v_mov_b64_e32 v[22:23], 0
	v_mov_b64_e32 v[24:25], 0
	v_mov_b64_e32 v[26:27], 0
	v_mov_b64_e32 v[28:29], 0
	v_mov_b64_e32 v[30:31], 0
	v_mov_b64_e32 v[32:33], 0
	v_mov_b64_e32 v[34:35], 0
	v_mov_b64_e32 v[36:37], 0
	v_mov_b64_e32 v[38:39], 0
	v_mov_b64_e32 v[40:41], 0
	v_mov_b64_e32 v[42:43], 0
	v_mov_b64_e32 v[44:45], 0
	v_mov_b64_e32 v[46:47], 0
	v_mov_b64_e32 v[48:49], 0
	v_mov_b64_e32 v[50:51], 0
	v_mov_b64_e32 v[52:53], 0
	v_mov_b64_e32 v[54:55], 0
	v_mov_b64_e32 v[56:57], 0
	v_mov_b64_e32 v[58:59], 0
	v_mov_b64_e32 v[60:61], 0
	v_mov_b64_e32 v[62:63], 0
	v_mov_b64_e32 v[64:65], 0
	v_mov_b64_e32 v[66:67], 0
	v_mov_b64_e32 v[68:69], 0
	v_mov_b64_e32 v[70:71], 0
	v_mov_b64_e32 v[72:73], 0
	v_mov_b64_e32 v[74:75], 0
	v_mov_b64_e32 v[76:77], 0
	v_mov_b64_e32 v[78:79], 0
	v_mov_b64_e32 v[80:81], 0
	v_mov_b64_e32 v[82:83], 0
	v_mov_b64_e32 v[84:85], 0
	v_mov_b64_e32 v[86:87], 0
	v_mov_b64_e32 v[88:89], 0
	v_mov_b64_e32 v[90:91], 0
	v_mov_b64_e32 v[92:93], 0
	v_mov_b64_e32 v[94:95], 0
	v_mov_b64_e32 v[96:97], 0
	v_mov_b64_e32 v[98:99], 0
	v_mov_b64_e32 v[100:101], 0
	v_mov_b64_e32 v[102:103], 0
	v_mov_b64_e32 v[104:105], 0
	v_mov_b64_e32 v[106:107], 0
	v_mov_b64_e32 v[108:109], 0
	v_mov_b64_e32 v[110:111], 0
	v_mov_b64_e32 v[112:113], 0
	v_mov_b64_e32 v[114:115], 0
	v_mov_b64_e32 v[116:117], 0
	v_mov_b64_e32 v[118:119], 0
	v_mov_b64_e32 v[120:121], 0
	v_mov_b64_e32 v[122:123], 0
	v_mov_b64_e32 v[124:125], 0
	v_mov_b64_e32 v[126:127], 0
	s_andn2_b64 vcc, exec, s[8:9]
	s_mov_b64 s[36:37], s[22:23]
	s_cbranch_vccz .LBB0_2091

; template <class Epi>
; __device__ __forceinline__ void gemm_phase(LAS unsigned char* lds, const Gemm g, const Sched& S, const Epi& E) {
;     ...
; #pragma unroll
;         for (int a = 0; a < 2; ++a)
; #pragma unroll
;             for (int b = 0; b < 2; ++b)
; #pragma unroll
;                 for (int m = 0; m < 4; ++m)
; #pragma unroll
;                     for (int n = 0; n < 2; ++n) acc[a][b][m][n] = (f32x4){0.f, 0.f, 0.f, 0.f};
;         cur = nxt; cA = nA; cB = nB; ++ui;
.LBB0_2154:
	v_mov_b64_e32 v[0:1], 0
	s_mov_b32 s53, s65
	s_mov_b32 s14, s66
	s_mov_b64 s[16:17], s[20:21]
	s_mov_b32 s52, s50
	v_mov_b64_e32 v[2:3], 0
	v_mov_b64_e32 v[4:5], 0
	v_mov_b64_e32 v[6:7], 0
	v_mov_b64_e32 v[8:9], 0
	v_mov_b64_e32 v[10:11], 0
	v_mov_b64_e32 v[12:13], 0
	v_mov_b64_e32 v[14:15], 0
	v_mov_b64_e32 v[16:17], 0
	v_mov_b64_e32 v[18:19], 0
	v_mov_b64_e32 v[20:21], 0
	v_mov_b64_e32 v[22:23], 0
	v_mov_b64_e32 v[24:25], 0
	v_mov_b64_e32 v[26:27], 0
	v_mov_b64_e32 v[28:29], 0
	v_mov_b64_e32 v[30:31], 0
	v_mov_b64_e32 v[32:33], 0
	v_mov_b64_e32 v[34:35], 0
	v_mov_b64_e32 v[36:37], 0
	v_mov_b64_e32 v[38:39], 0
	v_mov_b64_e32 v[40:41], 0
	v_mov_b64_e32 v[42:43], 0
	v_mov_b64_e32 v[44:45], 0
	v_mov_b64_e32 v[46:47], 0
	v_mov_b64_e32 v[48:49], 0
	v_mov_b64_e32 v[50:51], 0
	v_mov_b64_e32 v[52:53], 0
	v_mov_b64_e32 v[54:55], 0
	v_mov_b64_e32 v[56:57], 0
	v_mov_b64_e32 v[58:59], 0
	v_mov_b64_e32 v[60:61], 0
	v_mov_b64_e32 v[62:63], 0
	v_mov_b64_e32 v[64:65], 0
	v_mov_b64_e32 v[66:67], 0
	v_mov_b64_e32 v[68:69], 0
	v_mov_b64_e32 v[70:71], 0
	v_mov_b64_e32 v[72:73], 0
	v_mov_b64_e32 v[74:75], 0
	v_mov_b64_e32 v[76:77], 0
	v_mov_b64_e32 v[78:79], 0
	v_mov_b64_e32 v[80:81], 0
	v_mov_b64_e32 v[82:83], 0
	v_mov_b64_e32 v[84:85], 0
	v_mov_b64_e32 v[86:87], 0
	v_mov_b64_e32 v[88:89], 0
	v_mov_b64_e32 v[90:91], 0
	v_mov_b64_e32 v[92:93], 0
	v_mov_b64_e32 v[94:95], 0
	v_mov_b64_e32 v[96:97], 0
	v_mov_b64_e32 v[98:99], 0
	v_mov_b64_e32 v[100:101], 0
	v_mov_b64_e32 v[102:103], 0
	v_mov_b64_e32 v[104:105], 0
	v_mov_b64_e32 v[106:107], 0
	v_mov_b64_e32 v[108:109], 0
	v_mov_b64_e32 v[110:111], 0
	v_mov_b64_e32 v[112:113], 0
	v_mov_b64_e32 v[114:115], 0
	v_mov_b64_e32 v[116:117], 0
	v_mov_b64_e32 v[118:119], 0
	v_mov_b64_e32 v[120:121], 0
	v_mov_b64_e32 v[122:123], 0
	v_mov_b64_e32 v[124:125], 0
	v_mov_b64_e32 v[126:127], 0
	s_andn2_b64 vcc, exec, s[8:9]
	s_mov_b64 s[22:23], s[12:13]
	s_cbranch_vccz .LBB0_2169

; template <class Epi>
; __device__ __forceinline__ void gemm_phase(LAS unsigned char* lds, const Gemm g, const Sched& S, const Epi& E) {
;     ...
; #pragma unroll
;         for (int a = 0; a < 2; ++a)
; #pragma unroll
;             for (int b = 0; b < 2; ++b)
; #pragma unroll
;                 for (int m = 0; m < 4; ++m)
; #pragma unroll
;                     for (int n = 0; n < 2; ++n) acc[a][b][m][n] = (f32x4){0.f, 0.f, 0.f, 0.f};
;         cur = nxt; cA = nA; cB = nB; ++ui;
.LBB0_2484:
	v_mov_b64_e32 v[0:1], 0
	s_mov_b32 s18, s58
	s_mov_b32 s20, s64
	s_mov_b64 s[22:23], s[78:79]
	s_mov_b32 s43, s50
	v_mov_b64_e32 v[2:3], 0
	v_mov_b64_e32 v[4:5], 0
	v_mov_b64_e32 v[6:7], 0
	v_mov_b64_e32 v[8:9], 0
	v_mov_b64_e32 v[10:11], 0
	v_mov_b64_e32 v[12:13], 0
	v_mov_b64_e32 v[14:15], 0
	v_mov_b64_e32 v[16:17], 0
	v_mov_b64_e32 v[18:19], 0
	v_mov_b64_e32 v[20:21], 0
	v_mov_b64_e32 v[22:23], 0
	v_mov_b64_e32 v[24:25], 0
	v_mov_b64_e32 v[26:27], 0
	v_mov_b64_e32 v[28:29], 0
	v_mov_b64_e32 v[30:31], 0
	v_mov_b64_e32 v[32:33], 0
	v_mov_b64_e32 v[34:35], 0
	v_mov_b64_e32 v[36:37], 0
	v_mov_b64_e32 v[38:39], 0
	v_mov_b64_e32 v[40:41], 0
	v_mov_b64_e32 v[42:43], 0
	v_mov_b64_e32 v[44:45], 0
	v_mov_b64_e32 v[46:47], 0
	v_mov_b64_e32 v[48:49], 0
	v_mov_b64_e32 v[50:51], 0
	v_mov_b64_e32 v[52:53], 0
	v_mov_b64_e32 v[54:55], 0
	v_mov_b64_e32 v[56:57], 0
	v_mov_b64_e32 v[58:59], 0
	v_mov_b64_e32 v[60:61], 0
	v_mov_b64_e32 v[62:63], 0
	v_mov_b64_e32 v[64:65], 0
	v_mov_b64_e32 v[66:67], 0
	v_mov_b64_e32 v[68:69], 0
	v_mov_b64_e32 v[70:71], 0
	v_mov_b64_e32 v[72:73], 0
	v_mov_b64_e32 v[74:75], 0
	v_mov_b64_e32 v[76:77], 0
	v_mov_b64_e32 v[78:79], 0
	v_mov_b64_e32 v[80:81], 0
	v_mov_b64_e32 v[82:83], 0
	v_mov_b64_e32 v[84:85], 0
	v_mov_b64_e32 v[86:87], 0
	v_mov_b64_e32 v[88:89], 0
	v_mov_b64_e32 v[90:91], 0
	v_mov_b64_e32 v[92:93], 0
	v_mov_b64_e32 v[94:95], 0
	v_mov_b64_e32 v[96:97], 0
	v_mov_b64_e32 v[98:99], 0
	v_mov_b64_e32 v[100:101], 0
	v_mov_b64_e32 v[102:103], 0
	v_mov_b64_e32 v[104:105], 0
	v_mov_b64_e32 v[106:107], 0
	v_mov_b64_e32 v[108:109], 0
	v_mov_b64_e32 v[110:111], 0
	v_mov_b64_e32 v[112:113], 0
	v_mov_b64_e32 v[114:115], 0
	v_mov_b64_e32 v[116:117], 0
	v_mov_b64_e32 v[118:119], 0
	v_mov_b64_e32 v[120:121], 0
	v_mov_b64_e32 v[122:123], 0
	v_mov_b64_e32 v[124:125], 0
	v_mov_b64_e32 v[126:127], 0
	s_andn2_b64 vcc, exec, s[8:9]
	s_mov_b64 s[12:13], s[66:67]
	s_cbranch_vccz .LBB0_2555

;     __device__ __forceinline__ size_t a_off(const Unit& u) const { return (size_t)(u.z >> 3) * zA_hi + (size_t)(u.z & 7) * zA_lo + (size_t)u.pm * aTile; }
;     __device__ __forceinline__ size_t b_off(const Unit& u) const { return (size_t)(u.z >> 3) * zB_hi + (size_t)u.pn * bTile; }
; template <class Epi>
; __device__ __forceinline__ void gemm_phase(LAS unsigned char* lds, const Gemm g, const Sched& S, const Epi& E) {
;     ...
;         const bool has_next = S.next(ui + 1, nxt);
;         const char* nA = has_next ? (const char*)g.A + S.a_off(nxt) : cA; const char* nB = has_next ? (const char*)g.Bt + S.b_off(nxt) : cB;
;     ...
; #pragma unroll
;         for (int a = 0; a < 2; ++a)
; #pragma unroll
;             for (int b = 0; b < 2; ++b)
; #pragma unroll
;                 for (int m = 0; m < 4; ++m)
; #pragma unroll
;                     for (int n = 0; n < 2; ++n) acc[a][b][m][n] = (f32x4){0.f, 0.f, 0.f, 0.f};
;         cur = nxt; cA = nA; cB = nB; ++ui;
.LBB0_2674:
	s_ashr_i32 s59, s58, 31
	v_cmp_lt_i64_e32 vcc, s[16:17], v[206:207]
	s_lshl_b64 s[16:17], s[58:59], 18
	s_add_u32 s60, s33, s16
	s_addc_u32 s61, s34, s17
	s_and_b64 s[16:17], vcc, exec
	s_cselect_b32 s50, s61, s13
	s_cselect_b32 s51, s60, s12
	s_ashr_i32 s57, s56, 31
	s_lshl_b64 s[16:17], s[56:57], 18
	s_add_u32 s62, s74, s16
	s_addc_u32 s63, s75, s17
	s_and_b64 s[16:17], vcc, exec
	s_cselect_b32 s57, s63, s15
	s_cselect_b32 s59, s62, s14
	s_add_u32 s12, s12, 0x20080
	s_addc_u32 s13, s13, 0
	s_add_u32 s64, s14, 0x100
	v_mov_b64_e32 v[0:1], 0
	s_addc_u32 s65, s15, 0
	s_mov_b32 s84, -2
	v_mov_b64_e32 v[2:3], 0
	v_mov_b64_e32 v[4:5], 0
	v_mov_b64_e32 v[6:7], 0
	v_mov_b64_e32 v[12:13], 0
	v_mov_b64_e32 v[14:15], 0
	v_mov_b64_e32 v[20:21], 0
	v_mov_b64_e32 v[22:23], 0
	v_mov_b64_e32 v[28:29], 0
	v_mov_b64_e32 v[30:31], 0
	v_mov_b64_e32 v[36:37], 0
	v_mov_b64_e32 v[38:39], 0
	v_mov_b64_e32 v[44:45], 0
	v_mov_b64_e32 v[46:47], 0
	v_mov_b64_e32 v[52:53], 0
	v_mov_b64_e32 v[54:55], 0
	v_mov_b64_e32 v[8:9], 0
	v_mov_b64_e32 v[10:11], 0
	v_mov_b64_e32 v[16:17], 0
	v_mov_b64_e32 v[18:19], 0
	v_mov_b64_e32 v[24:25], 0
	v_mov_b64_e32 v[26:27], 0
	v_mov_b64_e32 v[32:33], 0
	v_mov_b64_e32 v[34:35], 0
	v_mov_b64_e32 v[40:41], 0
	v_mov_b64_e32 v[42:43], 0
	v_mov_b64_e32 v[48:49], 0
	v_mov_b64_e32 v[50:51], 0
	v_mov_b64_e32 v[56:57], 0
	v_mov_b64_e32 v[58:59], 0
	v_mov_b64_e32 v[60:61], 0
	v_mov_b64_e32 v[62:63], 0
	v_mov_b64_e32 v[64:65], 0
	v_mov_b64_e32 v[66:67], 0
	v_mov_b64_e32 v[68:69], 0
	v_mov_b64_e32 v[70:71], 0
	v_mov_b64_e32 v[76:77], 0
	v_mov_b64_e32 v[78:79], 0
	v_mov_b64_e32 v[84:85], 0
	v_mov_b64_e32 v[86:87], 0
	v_mov_b64_e32 v[92:93], 0
	v_mov_b64_e32 v[94:95], 0
	v_mov_b64_e32 v[100:101], 0
	v_mov_b64_e32 v[102:103], 0
	v_mov_b64_e32 v[112:113], 0
	v_mov_b64_e32 v[114:115], 0
	v_mov_b64_e32 v[124:125], 0
	v_mov_b64_e32 v[126:127], 0
	v_mov_b64_e32 v[72:73], 0
	v_mov_b64_e32 v[74:75], 0
	v_mov_b64_e32 v[80:81], 0
	v_mov_b64_e32 v[82:83], 0
	v_mov_b64_e32 v[88:89], 0
	v_mov_b64_e32 v[90:91], 0
	v_mov_b64_e32 v[96:97], 0
	v_mov_b64_e32 v[98:99], 0
	v_mov_b64_e32 v[108:109], 0
	v_mov_b64_e32 v[110:111], 0
	v_mov_b64_e32 v[116:117], 0
	v_mov_b64_e32 v[118:119], 0
	v_mov_b64_e32 v[136:137], 0
	v_mov_b64_e32 v[138:139], 0
	v_mov_b64_e32 v[148:149], 0
	v_mov_b64_e32 v[150:151], 0

;     __device__ __forceinline__ size_t a_off(const Unit& u) const { return (size_t)(u.z >> 3) * zA_hi + (size_t)(u.z & 7) * zA_lo + (size_t)u.pm * aTile; }
;     __device__ __forceinline__ size_t b_off(const Unit& u) const { return (size_t)(u.z >> 3) * zB_hi + (size_t)u.pn * bTile; }
; template <class Epi>
; __device__ __forceinline__ void gemm_phase(LAS unsigned char* lds, const Gemm g, const Sched& S, const Epi& E) {
;     ...
;         const bool has_next = S.next(ui + 1, nxt);
;         const char* nA = has_next ? (const char*)g.A + S.a_off(nxt) : cA; const char* nB = has_next ? (const char*)g.Bt + S.b_off(nxt) : cB;
;     ...
; #pragma unroll
;         for (int a = 0; a < 2; ++a)
; #pragma unroll
;             for (int b = 0; b < 2; ++b)
; #pragma unroll
;                 for (int m = 0; m < 4; ++m)
; #pragma unroll
;                     for (int n = 0; n < 2; ++n) acc[a][b][m][n] = (f32x4){0.f, 0.f, 0.f, 0.f};
;         cur = nxt; cA = nA; cB = nB; ++ui;
.LBB0_2709:
	s_ashr_i32 s15, s14, 31
	v_cmp_lt_i64_e32 vcc, s[16:17], v[142:143]
	s_lshl_b64 s[16:17], s[14:15], 18
	s_add_u32 s16, s33, s16
	s_addc_u32 s17, s34, s17
	s_and_b64 s[18:19], vcc, exec
	s_cselect_b32 s15, s17, s37
	s_cselect_b32 s25, s16, s36
	s_ashr_i32 s13, s12, 31
	s_lshl_b64 s[18:19], s[12:13], 18
	s_add_u32 s18, s72, s18
	s_addc_u32 s19, s73, s19
	s_and_b64 s[46:47], vcc, exec
	s_cselect_b32 s13, s19, s39
	s_cselect_b32 s70, s18, s38
	s_add_u32 s36, s36, 0x20080
	s_addc_u32 s37, s37, 0
	s_add_u32 s71, s38, 0x100
	v_mov_b64_e32 v[0:1], 0
	s_addc_u32 s74, s39, 0
	s_mov_b32 s75, -2
	v_mov_b64_e32 v[2:3], 0
	v_mov_b64_e32 v[4:5], 0
	v_mov_b64_e32 v[6:7], 0
	v_mov_b64_e32 v[12:13], 0
	v_mov_b64_e32 v[14:15], 0
	v_mov_b64_e32 v[20:21], 0
	v_mov_b64_e32 v[22:23], 0
	v_mov_b64_e32 v[28:29], 0
	v_mov_b64_e32 v[30:31], 0
	v_mov_b64_e32 v[36:37], 0
	v_mov_b64_e32 v[38:39], 0
	v_mov_b64_e32 v[44:45], 0
	v_mov_b64_e32 v[46:47], 0
	v_mov_b64_e32 v[52:53], 0
	v_mov_b64_e32 v[54:55], 0
	v_mov_b64_e32 v[8:9], 0
	v_mov_b64_e32 v[10:11], 0
	v_mov_b64_e32 v[16:17], 0
	v_mov_b64_e32 v[18:19], 0
	v_mov_b64_e32 v[24:25], 0
	v_mov_b64_e32 v[26:27], 0
	v_mov_b64_e32 v[32:33], 0
	v_mov_b64_e32 v[34:35], 0
	v_mov_b64_e32 v[40:41], 0
	v_mov_b64_e32 v[42:43], 0
	v_mov_b64_e32 v[48:49], 0
	v_mov_b64_e32 v[50:51], 0
	v_mov_b64_e32 v[56:57], 0
	v_mov_b64_e32 v[58:59], 0
	v_mov_b64_e32 v[60:61], 0
	v_mov_b64_e32 v[62:63], 0
	v_mov_b64_e32 v[64:65], 0
	v_mov_b64_e32 v[66:67], 0
	v_mov_b64_e32 v[68:69], 0
	v_mov_b64_e32 v[70:71], 0
	v_mov_b64_e32 v[76:77], 0
	v_mov_b64_e32 v[78:79], 0
	v_mov_b64_e32 v[84:85], 0
	v_mov_b64_e32 v[86:87], 0
	v_mov_b64_e32 v[92:93], 0
	v_mov_b64_e32 v[94:95], 0
	v_mov_b64_e32 v[100:101], 0
	v_mov_b64_e32 v[102:103], 0
	v_mov_b64_e32 v[108:109], 0
	v_mov_b64_e32 v[110:111], 0
	v_mov_b64_e32 v[116:117], 0
	v_mov_b64_e32 v[118:119], 0
	v_mov_b64_e32 v[72:73], 0
	v_mov_b64_e32 v[74:75], 0
	v_mov_b64_e32 v[80:81], 0
	v_mov_b64_e32 v[82:83], 0
	v_mov_b64_e32 v[88:89], 0
	v_mov_b64_e32 v[90:91], 0
	v_mov_b64_e32 v[96:97], 0
	v_mov_b64_e32 v[98:99], 0
	v_mov_b64_e32 v[104:105], 0
	v_mov_b64_e32 v[106:107], 0
	v_mov_b64_e32 v[112:113], 0
	v_mov_b64_e32 v[114:115], 0
	v_mov_b64_e32 v[120:121], 0
	v_mov_b64_e32 v[122:123], 0
	v_mov_b64_e32 v[124:125], 0
	v_mov_b64_e32 v[126:127], 0

; template <class Epi>
; __device__ __forceinline__ void gemm_phase(LAS unsigned char* lds, const Gemm g, const Sched& S, const Epi& E) {
;     ...
; #pragma unroll
;         for (int a = 0; a < 2; ++a)
; #pragma unroll
;             for (int b = 0; b < 2; ++b)
; #pragma unroll
;                 for (int m = 0; m < 4; ++m)
; #pragma unroll
;                     for (int n = 0; n < 2; ++n) acc[a][b][m][n] = (f32x4){0.f, 0.f, 0.f, 0.f};
;         cur = nxt; cA = nA; cB = nB; ++ui;
.LBB0_2956:
	v_mov_b64_e32 v[0:1], 0
	s_mov_b32 s53, s18
	s_mov_b32 s12, s20
	s_mov_b64 s[14:15], s[24:25]
	s_mov_b32 s52, s50
	v_mov_b64_e32 v[2:3], 0
	v_mov_b64_e32 v[4:5], 0
	v_mov_b64_e32 v[6:7], 0
	v_mov_b64_e32 v[8:9], 0
	v_mov_b64_e32 v[10:11], 0
	v_mov_b64_e32 v[12:13], 0
	v_mov_b64_e32 v[14:15], 0
	v_mov_b64_e32 v[16:17], 0
	v_mov_b64_e32 v[18:19], 0
	v_mov_b64_e32 v[20:21], 0
	v_mov_b64_e32 v[22:23], 0
	v_mov_b64_e32 v[24:25], 0
	v_mov_b64_e32 v[26:27], 0
	v_mov_b64_e32 v[28:29], 0
	v_mov_b64_e32 v[30:31], 0
	v_mov_b64_e32 v[32:33], 0
	v_mov_b64_e32 v[34:35], 0
	v_mov_b64_e32 v[36:37], 0
	v_mov_b64_e32 v[38:39], 0
	v_mov_b64_e32 v[40:41], 0
	v_mov_b64_e32 v[42:43], 0
	v_mov_b64_e32 v[44:45], 0
	v_mov_b64_e32 v[46:47], 0
	v_mov_b64_e32 v[48:49], 0
	v_mov_b64_e32 v[50:51], 0
	v_mov_b64_e32 v[52:53], 0
	v_mov_b64_e32 v[54:55], 0
	v_mov_b64_e32 v[56:57], 0
	v_mov_b64_e32 v[58:59], 0
	v_mov_b64_e32 v[60:61], 0
	v_mov_b64_e32 v[62:63], 0
	v_mov_b64_e32 v[64:65], 0
	v_mov_b64_e32 v[66:67], 0
	v_mov_b64_e32 v[68:69], 0
	v_mov_b64_e32 v[70:71], 0
	v_mov_b64_e32 v[72:73], 0
	v_mov_b64_e32 v[74:75], 0
	v_mov_b64_e32 v[76:77], 0
	v_mov_b64_e32 v[78:79], 0
	v_mov_b64_e32 v[80:81], 0
	v_mov_b64_e32 v[82:83], 0
	v_mov_b64_e32 v[84:85], 0
	v_mov_b64_e32 v[86:87], 0
	v_mov_b64_e32 v[88:89], 0
	v_mov_b64_e32 v[90:91], 0
	v_mov_b64_e32 v[92:93], 0
	v_mov_b64_e32 v[94:95], 0
	v_mov_b64_e32 v[96:97], 0
	v_mov_b64_e32 v[98:99], 0
	v_mov_b64_e32 v[100:101], 0
	v_mov_b64_e32 v[102:103], 0
	v_mov_b64_e32 v[104:105], 0
	v_mov_b64_e32 v[106:107], 0
	v_mov_b64_e32 v[108:109], 0
	v_mov_b64_e32 v[110:111], 0
	v_mov_b64_e32 v[112:113], 0
	v_mov_b64_e32 v[114:115], 0
	v_mov_b64_e32 v[116:117], 0
	v_mov_b64_e32 v[118:119], 0
	v_mov_b64_e32 v[120:121], 0
	v_mov_b64_e32 v[122:123], 0
	v_mov_b64_e32 v[124:125], 0
	v_mov_b64_e32 v[126:127], 0
	s_andn2_b64 vcc, exec, s[8:9]
	s_mov_b64 s[36:37], s[22:23]
	s_cbranch_vccz .LBB0_2967

; template <class Epi>
; __device__ __forceinline__ void gemm_phase(LAS unsigned char* lds, const Gemm g, const Sched& S, const Epi& E) {
;     ...
; #pragma unroll
;         for (int a = 0; a < 2; ++a)
; #pragma unroll
;             for (int b = 0; b < 2; ++b)
; #pragma unroll
;                 for (int m = 0; m < 4; ++m)
; #pragma unroll
;                     for (int n = 0; n < 2; ++n) acc[a][b][m][n] = (f32x4){0.f, 0.f, 0.f, 0.f};
;         cur = nxt; cA = nA; cB = nB; ++ui;
.LBB0_3081:
	v_mov_b64_e32 v[0:1], 0
	s_mov_b32 s50, s16
	s_mov_b32 s10, s18
	s_mov_b64 s[12:13], s[22:23]
	s_mov_b32 s47, s63
	v_mov_b64_e32 v[2:3], 0
	v_mov_b64_e32 v[4:5], 0
	v_mov_b64_e32 v[6:7], 0
	v_mov_b64_e32 v[8:9], 0
	v_mov_b64_e32 v[10:11], 0
	v_mov_b64_e32 v[12:13], 0
	v_mov_b64_e32 v[14:15], 0
	v_mov_b64_e32 v[16:17], 0
	v_mov_b64_e32 v[18:19], 0
	v_mov_b64_e32 v[20:21], 0
	v_mov_b64_e32 v[22:23], 0
	v_mov_b64_e32 v[24:25], 0
	v_mov_b64_e32 v[26:27], 0
	v_mov_b64_e32 v[28:29], 0
	v_mov_b64_e32 v[30:31], 0
	v_mov_b64_e32 v[32:33], 0
	v_mov_b64_e32 v[34:35], 0
	v_mov_b64_e32 v[36:37], 0
	v_mov_b64_e32 v[38:39], 0
	v_mov_b64_e32 v[40:41], 0
	v_mov_b64_e32 v[42:43], 0
	v_mov_b64_e32 v[44:45], 0
	v_mov_b64_e32 v[46:47], 0
	v_mov_b64_e32 v[48:49], 0
	v_mov_b64_e32 v[50:51], 0
	v_mov_b64_e32 v[52:53], 0
	v_mov_b64_e32 v[54:55], 0
	v_mov_b64_e32 v[56:57], 0
	v_mov_b64_e32 v[58:59], 0
	v_mov_b64_e32 v[60:61], 0
	v_mov_b64_e32 v[62:63], 0
	v_mov_b64_e32 v[64:65], 0
	v_mov_b64_e32 v[66:67], 0
	v_mov_b64_e32 v[68:69], 0
	v_mov_b64_e32 v[70:71], 0
	v_mov_b64_e32 v[72:73], 0
	v_mov_b64_e32 v[74:75], 0
	v_mov_b64_e32 v[76:77], 0
	v_mov_b64_e32 v[78:79], 0
	v_mov_b64_e32 v[80:81], 0
	v_mov_b64_e32 v[82:83], 0
	v_mov_b64_e32 v[84:85], 0
	v_mov_b64_e32 v[86:87], 0
	v_mov_b64_e32 v[88:89], 0
	v_mov_b64_e32 v[90:91], 0
	v_mov_b64_e32 v[92:93], 0
	v_mov_b64_e32 v[94:95], 0
	v_mov_b64_e32 v[96:97], 0
	v_mov_b64_e32 v[98:99], 0
	v_mov_b64_e32 v[100:101], 0
	v_mov_b64_e32 v[102:103], 0
	v_mov_b64_e32 v[104:105], 0
	v_mov_b64_e32 v[106:107], 0
	v_mov_b64_e32 v[108:109], 0
	v_mov_b64_e32 v[110:111], 0
	v_mov_b64_e32 v[112:113], 0
	v_mov_b64_e32 v[114:115], 0
	v_mov_b64_e32 v[116:117], 0
	v_mov_b64_e32 v[118:119], 0
	v_mov_b64_e32 v[120:121], 0
	v_mov_b64_e32 v[122:123], 0
	v_mov_b64_e32 v[124:125], 0
	v_mov_b64_e32 v[126:127], 0
	s_andn2_b64 vcc, exec, s[6:7]
	s_mov_b64 s[24:25], s[20:21]
	s_cbranch_vccz .LBB0_3088

; template <class Epi>
; __device__ __forceinline__ void gemm_phase(LAS unsigned char* lds, const Gemm g, const Sched& S, const Epi& E) {
;     ...
; #pragma unroll
;         for (int a = 0; a < 2; ++a)
; #pragma unroll
;             for (int b = 0; b < 2; ++b)
; #pragma unroll
;                 for (int m = 0; m < 4; ++m)
; #pragma unroll
;                     for (int n = 0; n < 2; ++n) acc[a][b][m][n] = (f32x4){0.f, 0.f, 0.f, 0.f};
;         cur = nxt; cA = nA; cB = nB; ++ui;
.LBB0_3151:
	v_mov_b64_e32 v[0:1], 0
	s_mov_b32 s38, s53
	s_mov_b32 s10, s54
	s_mov_b64 s[12:13], s[16:17]
	s_mov_b32 s37, s55
	v_mov_b64_e32 v[2:3], 0
	v_mov_b64_e32 v[4:5], 0
	v_mov_b64_e32 v[6:7], 0
	v_mov_b64_e32 v[8:9], 0
	v_mov_b64_e32 v[10:11], 0
	v_mov_b64_e32 v[12:13], 0
	v_mov_b64_e32 v[14:15], 0
	v_mov_b64_e32 v[16:17], 0
	v_mov_b64_e32 v[18:19], 0
	v_mov_b64_e32 v[20:21], 0
	v_mov_b64_e32 v[22:23], 0
	v_mov_b64_e32 v[24:25], 0
	v_mov_b64_e32 v[26:27], 0
	v_mov_b64_e32 v[28:29], 0
	v_mov_b64_e32 v[30:31], 0
	v_mov_b64_e32 v[32:33], 0
	v_mov_b64_e32 v[34:35], 0
	v_mov_b64_e32 v[36:37], 0
	v_mov_b64_e32 v[38:39], 0
	v_mov_b64_e32 v[40:41], 0
	v_mov_b64_e32 v[42:43], 0
	v_mov_b64_e32 v[44:45], 0
	v_mov_b64_e32 v[46:47], 0
	v_mov_b64_e32 v[48:49], 0
	v_mov_b64_e32 v[50:51], 0
	v_mov_b64_e32 v[52:53], 0
	v_mov_b64_e32 v[54:55], 0
	v_mov_b64_e32 v[56:57], 0
	v_mov_b64_e32 v[58:59], 0
	v_mov_b64_e32 v[60:61], 0
	v_mov_b64_e32 v[62:63], 0
	v_mov_b64_e32 v[64:65], 0
	v_mov_b64_e32 v[66:67], 0
	v_mov_b64_e32 v[68:69], 0
	v_mov_b64_e32 v[70:71], 0
	v_mov_b64_e32 v[72:73], 0
	v_mov_b64_e32 v[74:75], 0
	v_mov_b64_e32 v[76:77], 0
	v_mov_b64_e32 v[78:79], 0
	v_mov_b64_e32 v[80:81], 0
	v_mov_b64_e32 v[82:83], 0
	v_mov_b64_e32 v[84:85], 0
	v_mov_b64_e32 v[86:87], 0
	v_mov_b64_e32 v[88:89], 0
	v_mov_b64_e32 v[90:91], 0
	v_mov_b64_e32 v[92:93], 0
	v_mov_b64_e32 v[94:95], 0
	v_mov_b64_e32 v[96:97], 0
	v_mov_b64_e32 v[98:99], 0
	v_mov_b64_e32 v[100:101], 0
	v_mov_b64_e32 v[102:103], 0
	v_mov_b64_e32 v[104:105], 0
	v_mov_b64_e32 v[106:107], 0
	v_mov_b64_e32 v[108:109], 0
	v_mov_b64_e32 v[110:111], 0
	v_mov_b64_e32 v[112:113], 0
	v_mov_b64_e32 v[114:115], 0
	v_mov_b64_e32 v[116:117], 0
	v_mov_b64_e32 v[118:119], 0
	v_mov_b64_e32 v[120:121], 0
	v_mov_b64_e32 v[122:123], 0
	v_mov_b64_e32 v[124:125], 0
	v_mov_b64_e32 v[126:127], 0
	s_andn2_b64 vcc, exec, s[4:5]
	s_mov_b64 s[18:19], s[8:9]
	s_cbranch_vccz .LBB0_3166
